# IN GEMM K-loop: LDS-DMA loads use SGPR-base form and are issued at the start of each load segment, before the ds_reads
# speedup vs baseline: 1.0452x; 1.0017x over previous
.LBB0_920:
	s_add_u32 s2, s70, 0xfffc0080
	s_addc_u32 s3, s71, -1
	s_add_i32 s9, 0, 0x10000
	s_cmp_eq_u32 vcc_hi, 12
	s_cselect_b32 s75, s14, s3
	s_cselect_b32 s74, s24, s2
	s_cselect_b32 s73, s59, vcc_lo
	s_cselect_b32 s72, s61, s63
	s_add_i32 s0, 0, 0x14000
	s_add_i32 m0, s69, 0xc000
	s_nop 0

	global_load_lds_dwordx4 v172, s[70:71]
	s_add_i32 m0, s69, 0xe000
	s_nop 0
	global_load_lds_dwordx4 v174, s[70:71]
	v_add_u32_e32 v2, s9, v188
	ds_read_b128 v[132:135], v2
	ds_read_b128 v[136:139], v2 offset:1024
	ds_read_b128 v[140:143], v2 offset:2048
	ds_read_b128 v[144:147], v2 offset:3072
	v_add_u32_e32 v2, s0, v188
	ds_read_b128 v[148:151], v2
	ds_read_b128 v[152:155], v2 offset:1024
	ds_read_b128 v[156:159], v2 offset:2048
	ds_read_b128 v[160:163], v2 offset:3072
	v_lshl_add_u64 v[184:185], s[70:71], 0, v[172:173]
	ds_read_b128 v[176:179], v189
	ds_read_b128 v[180:183], v189 offset:1024
	ds_read_b128 v[198:201], v189 offset:2048
	ds_read_b128 v[202:205], v189 offset:3072
	ds_read_b128 v[206:209], v189 offset:4096
	ds_read_b128 v[210:213], v189 offset:5120
	ds_read_b128 v[214:217], v189 offset:6144
	ds_read_b128 v[218:221], v189 offset:7168
	v_lshl_add_u64 v[184:185], s[70:71], 0, v[174:175]
	s_waitcnt vmcnt(8)
	s_waitcnt lgkmcnt(0)
	s_barrier
	s_setprio 1
	s_waitcnt lgkmcnt(0)
	v_mfma_f32_16x16x32_bf16 v[128:131], v[132:135], v[176:179], v[128:131]
	v_mfma_f32_16x16x32_bf16 v[124:127], v[140:143], v[176:179], v[124:127]
	v_mfma_f32_16x16x32_bf16 v[112:115], v[132:135], v[198:201], v[112:115]
	v_mfma_f32_16x16x32_bf16 v[108:111], v[140:143], v[198:201], v[108:111]
	v_mfma_f32_16x16x32_bf16 v[96:99], v[132:135], v[206:209], v[96:99]
	v_mfma_f32_16x16x32_bf16 v[92:95], v[140:143], v[206:209], v[92:95]
	v_mfma_f32_16x16x32_bf16 v[80:83], v[132:135], v[214:217], v[80:83]
	v_mfma_f32_16x16x32_bf16 v[76:79], v[140:143], v[214:217], v[76:79]
	v_mfma_f32_16x16x32_bf16 v[128:131], v[136:139], v[180:183], v[128:131]
	v_mfma_f32_16x16x32_bf16 v[124:127], v[144:147], v[180:183], v[124:127]
	v_mfma_f32_16x16x32_bf16 v[112:115], v[136:139], v[202:205], v[112:115]
	v_mfma_f32_16x16x32_bf16 v[108:111], v[144:147], v[202:205], v[108:111]
	v_mfma_f32_16x16x32_bf16 v[96:99], v[136:139], v[210:213], v[96:99]
	v_mfma_f32_16x16x32_bf16 v[92:95], v[144:147], v[210:213], v[92:95]
	v_mfma_f32_16x16x32_bf16 v[80:83], v[136:139], v[218:221], v[80:83]
	v_mfma_f32_16x16x32_bf16 v[76:79], v[144:147], v[218:221], v[76:79]
	s_setprio 0
	s_setprio 1
	v_mfma_f32_16x16x32_bf16 v[120:123], v[148:151], v[176:179], v[120:123]
	v_mfma_f32_16x16x32_bf16 v[116:119], v[156:159], v[176:179], v[116:119]
	v_mfma_f32_16x16x32_bf16 v[104:107], v[148:151], v[198:201], v[104:107]
	v_mfma_f32_16x16x32_bf16 v[100:103], v[156:159], v[198:201], v[100:103]
	v_mfma_f32_16x16x32_bf16 v[88:91], v[148:151], v[206:209], v[88:91]
	v_mfma_f32_16x16x32_bf16 v[84:87], v[156:159], v[206:209], v[84:87]
	v_mfma_f32_16x16x32_bf16 v[72:75], v[148:151], v[214:217], v[72:75]
	v_mfma_f32_16x16x32_bf16 v[68:71], v[156:159], v[214:217], v[68:71]
	v_mfma_f32_16x16x32_bf16 v[120:123], v[152:155], v[180:183], v[120:123]
	v_mfma_f32_16x16x32_bf16 v[116:119], v[160:163], v[180:183], v[116:119]
	v_mfma_f32_16x16x32_bf16 v[104:107], v[152:155], v[202:205], v[104:107]
	v_mfma_f32_16x16x32_bf16 v[100:103], v[160:163], v[202:205], v[100:103]
	v_mfma_f32_16x16x32_bf16 v[88:91], v[152:155], v[210:213], v[88:91]
	v_mfma_f32_16x16x32_bf16 v[84:87], v[160:163], v[210:213], v[84:87]
	v_mfma_f32_16x16x32_bf16 v[72:75], v[152:155], v[218:221], v[72:75]
	v_mfma_f32_16x16x32_bf16 v[68:71], v[160:163], v[218:221], v[68:71]
	s_setprio 0
	s_barrier
	s_add_i32 s2, s9, s80
	s_mov_b32 m0, s2
	s_nop 0

	global_load_lds_dwordx4 v166, s[72:73]
	s_add_i32 m0, s2, 0x2000
	s_add_u32 s2, s72, 0x40000
	s_addc_u32 s3, s73, 0
	s_add_i32 s0, s0, s80
	global_load_lds_dwordx4 v170, s[72:73]
	s_mov_b32 m0, s0
	s_nop 0

	global_load_lds_dwordx4 v166, s[2:3]
	s_add_i32 m0, s0, 0x2000
	s_nop 0
	global_load_lds_dwordx4 v170, s[2:3]
	s_mov_b32 m0, s69
	s_nop 0
	global_load_lds_dwordx4 v164, s[74:75]
	s_mov_b32 m0, s81
	s_nop 0
	global_load_lds_dwordx4 v168, s[74:75]
	v_lshl_add_u64 v[184:185], s[72:73], 0, v[166:167]
	ds_read_b128 v[176:179], v189 offset:16384
	ds_read_b128 v[180:183], v189 offset:17408
	ds_read_b128 v[198:201], v189 offset:18432
	ds_read_b128 v[202:205], v189 offset:19456
	ds_read_b128 v[206:209], v189 offset:20480
	ds_read_b128 v[210:213], v189 offset:21504
	ds_read_b128 v[214:217], v189 offset:22528
	ds_read_b128 v[218:221], v189 offset:23552
	v_lshl_add_u64 v[190:191], s[72:73], 0, v[170:171]
	v_lshl_add_u64 v[222:223], s[2:3], 0, v[166:167]
	v_lshl_add_u64 v[224:225], s[74:75], 0, v[168:169]
	v_lshl_add_u64 v[222:223], s[2:3], 0, v[170:171]
	v_lshl_add_u64 v[222:223], s[74:75], 0, v[164:165]
	s_waitcnt vmcnt(8)
	s_waitcnt lgkmcnt(0)
	s_barrier
	s_setprio 1
	s_waitcnt lgkmcnt(0)
	v_mfma_f32_16x16x32_bf16 v[64:67], v[132:135], v[176:179], v[64:67]
	v_mfma_f32_16x16x32_bf16 v[60:63], v[140:143], v[176:179], v[60:63]
	v_mfma_f32_16x16x32_bf16 v[48:51], v[132:135], v[198:201], v[48:51]
	v_mfma_f32_16x16x32_bf16 v[44:47], v[140:143], v[198:201], v[44:47]
	v_mfma_f32_16x16x32_bf16 v[32:35], v[132:135], v[206:209], v[32:35]
	v_mfma_f32_16x16x32_bf16 v[28:31], v[140:143], v[206:209], v[28:31]
	v_mfma_f32_16x16x32_bf16 v[16:19], v[132:135], v[214:217], v[16:19]
	v_mfma_f32_16x16x32_bf16 v[12:15], v[140:143], v[214:217], v[12:15]
	v_mfma_f32_16x16x32_bf16 v[64:67], v[136:139], v[180:183], v[64:67]
	v_mfma_f32_16x16x32_bf16 v[60:63], v[144:147], v[180:183], v[60:63]
	v_mfma_f32_16x16x32_bf16 v[48:51], v[136:139], v[202:205], v[48:51]
	v_mfma_f32_16x16x32_bf16 v[44:47], v[144:147], v[202:205], v[44:47]
	v_mfma_f32_16x16x32_bf16 v[32:35], v[136:139], v[210:213], v[32:35]
	v_mfma_f32_16x16x32_bf16 v[28:31], v[144:147], v[210:213], v[28:31]
	v_mfma_f32_16x16x32_bf16 v[16:19], v[136:139], v[218:221], v[16:19]
	v_mfma_f32_16x16x32_bf16 v[12:15], v[144:147], v[218:221], v[12:15]
	s_setprio 0
	s_setprio 1
	v_mfma_f32_16x16x32_bf16 v[56:59], v[148:151], v[176:179], v[56:59]
	v_mfma_f32_16x16x32_bf16 v[52:55], v[156:159], v[176:179], v[52:55]
	v_mfma_f32_16x16x32_bf16 v[40:43], v[148:151], v[198:201], v[40:43]
	v_mfma_f32_16x16x32_bf16 v[36:39], v[156:159], v[198:201], v[36:39]
	v_mfma_f32_16x16x32_bf16 v[24:27], v[148:151], v[206:209], v[24:27]
	v_mfma_f32_16x16x32_bf16 v[20:23], v[156:159], v[206:209], v[20:23]
	v_mfma_f32_16x16x32_bf16 v[8:11], v[148:151], v[214:217], v[8:11]
	v_mfma_f32_16x16x32_bf16 v[4:7], v[156:159], v[214:217], v[4:7]
	v_mfma_f32_16x16x32_bf16 v[56:59], v[152:155], v[180:183], v[56:59]
	v_mfma_f32_16x16x32_bf16 v[52:55], v[160:163], v[180:183], v[52:55]
	v_mfma_f32_16x16x32_bf16 v[40:43], v[152:155], v[202:205], v[40:43]
	v_mfma_f32_16x16x32_bf16 v[36:39], v[160:163], v[202:205], v[36:39]
	v_mfma_f32_16x16x32_bf16 v[24:27], v[152:155], v[210:213], v[24:27]
	v_mfma_f32_16x16x32_bf16 v[20:23], v[160:163], v[210:213], v[20:23]
	v_mfma_f32_16x16x32_bf16 v[8:11], v[152:155], v[218:221], v[8:11]
	v_mfma_f32_16x16x32_bf16 v[4:7], v[160:163], v[218:221], v[4:7]
	s_setprio 0
	s_barrier
	s_add_i32 s0, 0, 0x18000
	s_add_i32 s9, 0, 0x1c000
	s_add_u32 s2, s74, 0x40000
	s_addc_u32 s3, s75, 0
	s_mov_b32 m0, s88
	s_nop 0

	global_load_lds_dwordx4 v164, s[2:3]
	s_mov_b32 m0, s89
	s_nop 0
	global_load_lds_dwordx4 v168, s[2:3]
	v_add_u32_e32 v2, s0, v188
	ds_read_b128 v[132:135], v2
	ds_read_b128 v[136:139], v2 offset:1024
	ds_read_b128 v[140:143], v2 offset:2048
	ds_read_b128 v[144:147], v2 offset:3072
	v_add_u32_e32 v2, s9, v188
	ds_read_b128 v[148:151], v2
	ds_read_b128 v[152:155], v2 offset:1024
	ds_read_b128 v[156:159], v2 offset:2048
	ds_read_b128 v[160:163], v2 offset:3072
	v_lshl_add_u64 v[226:227], s[2:3], 0, v[164:165]
	ds_read_b128 v[176:179], v189 offset:32768
	ds_read_b128 v[180:183], v189 offset:33792
	ds_read_b128 v[198:201], v189 offset:34816
	ds_read_b128 v[202:205], v189 offset:35840
	ds_read_b128 v[206:209], v189 offset:36864
	ds_read_b128 v[210:213], v189 offset:37888
	ds_read_b128 v[214:217], v189 offset:38912
	ds_read_b128 v[218:221], v189 offset:39936
	v_lshl_add_u64 v[226:227], s[2:3], 0, v[168:169]
	s_waitcnt vmcnt(8)
	s_waitcnt lgkmcnt(0)
	s_barrier
	s_setprio 1
	s_waitcnt lgkmcnt(0)
	v_mfma_f32_16x16x32_bf16 v[128:131], v[132:135], v[176:179], v[128:131]
	v_mfma_f32_16x16x32_bf16 v[124:127], v[140:143], v[176:179], v[124:127]
	v_mfma_f32_16x16x32_bf16 v[112:115], v[132:135], v[198:201], v[112:115]
	v_mfma_f32_16x16x32_bf16 v[108:111], v[140:143], v[198:201], v[108:111]
	v_mfma_f32_16x16x32_bf16 v[96:99], v[132:135], v[206:209], v[96:99]
	v_mfma_f32_16x16x32_bf16 v[92:95], v[140:143], v[206:209], v[92:95]
	v_mfma_f32_16x16x32_bf16 v[80:83], v[132:135], v[214:217], v[80:83]
	v_mfma_f32_16x16x32_bf16 v[76:79], v[140:143], v[214:217], v[76:79]
	v_mfma_f32_16x16x32_bf16 v[128:131], v[136:139], v[180:183], v[128:131]
	v_mfma_f32_16x16x32_bf16 v[124:127], v[144:147], v[180:183], v[124:127]
	v_mfma_f32_16x16x32_bf16 v[112:115], v[136:139], v[202:205], v[112:115]
	v_mfma_f32_16x16x32_bf16 v[108:111], v[144:147], v[202:205], v[108:111]
	v_mfma_f32_16x16x32_bf16 v[96:99], v[136:139], v[210:213], v[96:99]
	v_mfma_f32_16x16x32_bf16 v[92:95], v[144:147], v[210:213], v[92:95]
	v_mfma_f32_16x16x32_bf16 v[80:83], v[136:139], v[218:221], v[80:83]
	v_mfma_f32_16x16x32_bf16 v[76:79], v[144:147], v[218:221], v[76:79]
	s_setprio 0
	s_setprio 1
	v_mfma_f32_16x16x32_bf16 v[120:123], v[148:151], v[176:179], v[120:123]
	v_mfma_f32_16x16x32_bf16 v[116:119], v[156:159], v[176:179], v[116:119]
	v_mfma_f32_16x16x32_bf16 v[104:107], v[148:151], v[198:201], v[104:107]
	v_mfma_f32_16x16x32_bf16 v[100:103], v[156:159], v[198:201], v[100:103]
	v_mfma_f32_16x16x32_bf16 v[88:91], v[148:151], v[206:209], v[88:91]
	v_mfma_f32_16x16x32_bf16 v[84:87], v[156:159], v[206:209], v[84:87]
	v_mfma_f32_16x16x32_bf16 v[72:75], v[148:151], v[214:217], v[72:75]
	v_mfma_f32_16x16x32_bf16 v[68:71], v[156:159], v[214:217], v[68:71]
	v_mfma_f32_16x16x32_bf16 v[120:123], v[152:155], v[180:183], v[120:123]
	v_mfma_f32_16x16x32_bf16 v[116:119], v[160:163], v[180:183], v[116:119]
	v_mfma_f32_16x16x32_bf16 v[104:107], v[152:155], v[202:205], v[104:107]
	v_mfma_f32_16x16x32_bf16 v[100:103], v[160:163], v[202:205], v[100:103]
	v_mfma_f32_16x16x32_bf16 v[88:91], v[152:155], v[210:213], v[88:91]
	v_mfma_f32_16x16x32_bf16 v[84:87], v[160:163], v[210:213], v[84:87]
	v_mfma_f32_16x16x32_bf16 v[72:75], v[152:155], v[218:221], v[72:75]
	v_mfma_f32_16x16x32_bf16 v[68:71], v[160:163], v[218:221], v[68:71]
	s_setprio 0
	s_barrier
	s_add_u32 s98, s72, 0x80
	s_addc_u32 s99, s73, 0
	s_add_u32 s100, s74, 0x80
	s_addc_u32 s101, s75, 0
	s_add_i32 s0, s0, s80
	s_mov_b32 m0, s0
	s_nop 0

	global_load_lds_dwordx4 v166, s[98:99]
	s_add_i32 m0, s0, 0x2000
	s_add_u32 s2, s72, 0x40080
	s_addc_u32 s3, s73, 0
	s_add_i32 s0, s9, s80
	global_load_lds_dwordx4 v170, s[98:99]
	s_mov_b32 m0, s0
	s_nop 0
	global_load_lds_dwordx4 v166, s[2:3]
	s_add_i32 m0, s0, 0x2000
	s_nop 0
	global_load_lds_dwordx4 v170, s[2:3]
	s_mov_b32 m0, s92
	s_nop 0
	global_load_lds_dwordx4 v164, s[100:101]
	s_mov_b32 m0, s93
	s_nop 0
	global_load_lds_dwordx4 v168, s[100:101]
	v_lshl_add_u64 v[184:185], v[184:185], 0, s[26:27]
	ds_read_b128 v[176:179], v189 offset:49152
	ds_read_b128 v[180:183], v189 offset:50176
	ds_read_b128 v[198:201], v189 offset:51200
	ds_read_b128 v[202:205], v189 offset:52224
	ds_read_b128 v[206:209], v189 offset:53248
	ds_read_b128 v[210:213], v189 offset:54272
	ds_read_b128 v[214:217], v189 offset:55296
	ds_read_b128 v[218:221], v189 offset:56320
	v_lshl_add_u64 v[184:185], v[190:191], 0, s[26:27]
	v_lshl_add_u64 v[184:185], s[2:3], 0, v[166:167]
	v_lshl_add_u64 v[184:185], s[2:3], 0, v[170:171]
	v_lshl_add_u64 v[184:185], v[222:223], 0, s[26:27]
	v_lshl_add_u64 v[184:185], v[224:225], 0, s[26:27]
	s_waitcnt vmcnt(8)
	s_waitcnt lgkmcnt(0)
	s_barrier
	s_setprio 1
	s_waitcnt lgkmcnt(0)
	v_mfma_f32_16x16x32_bf16 v[64:67], v[132:135], v[176:179], v[64:67]
	v_mfma_f32_16x16x32_bf16 v[60:63], v[140:143], v[176:179], v[60:63]
	v_mfma_f32_16x16x32_bf16 v[48:51], v[132:135], v[198:201], v[48:51]
	v_mfma_f32_16x16x32_bf16 v[44:47], v[140:143], v[198:201], v[44:47]
	v_mfma_f32_16x16x32_bf16 v[32:35], v[132:135], v[206:209], v[32:35]
	v_mfma_f32_16x16x32_bf16 v[28:31], v[140:143], v[206:209], v[28:31]
	v_mfma_f32_16x16x32_bf16 v[16:19], v[132:135], v[214:217], v[16:19]
	v_mfma_f32_16x16x32_bf16 v[12:15], v[140:143], v[214:217], v[12:15]
	v_mfma_f32_16x16x32_bf16 v[64:67], v[136:139], v[180:183], v[64:67]
	v_mfma_f32_16x16x32_bf16 v[60:63], v[144:147], v[180:183], v[60:63]
	v_mfma_f32_16x16x32_bf16 v[48:51], v[136:139], v[202:205], v[48:51]
	v_mfma_f32_16x16x32_bf16 v[44:47], v[144:147], v[202:205], v[44:47]
	v_mfma_f32_16x16x32_bf16 v[32:35], v[136:139], v[210:213], v[32:35]
	v_mfma_f32_16x16x32_bf16 v[28:31], v[144:147], v[210:213], v[28:31]
	v_mfma_f32_16x16x32_bf16 v[16:19], v[136:139], v[218:221], v[16:19]
	v_mfma_f32_16x16x32_bf16 v[12:15], v[144:147], v[218:221], v[12:15]
	s_setprio 0
	s_setprio 1
	v_mfma_f32_16x16x32_bf16 v[56:59], v[148:151], v[176:179], v[56:59]
	v_mfma_f32_16x16x32_bf16 v[52:55], v[156:159], v[176:179], v[52:55]
	v_mfma_f32_16x16x32_bf16 v[40:43], v[148:151], v[198:201], v[40:43]
	v_mfma_f32_16x16x32_bf16 v[36:39], v[156:159], v[198:201], v[36:39]
	v_mfma_f32_16x16x32_bf16 v[24:27], v[148:151], v[206:209], v[24:27]
	v_mfma_f32_16x16x32_bf16 v[20:23], v[156:159], v[206:209], v[20:23]
	v_mfma_f32_16x16x32_bf16 v[8:11], v[148:151], v[214:217], v[8:11]
	v_mfma_f32_16x16x32_bf16 v[4:7], v[156:159], v[214:217], v[4:7]
	v_mfma_f32_16x16x32_bf16 v[56:59], v[152:155], v[180:183], v[56:59]
	v_mfma_f32_16x16x32_bf16 v[52:55], v[160:163], v[180:183], v[52:55]
	v_mfma_f32_16x16x32_bf16 v[40:43], v[152:155], v[202:205], v[40:43]
	v_mfma_f32_16x16x32_bf16 v[36:39], v[160:163], v[202:205], v[36:39]
	v_mfma_f32_16x16x32_bf16 v[24:27], v[152:155], v[210:213], v[24:27]
	v_mfma_f32_16x16x32_bf16 v[20:23], v[160:163], v[210:213], v[20:23]
	v_mfma_f32_16x16x32_bf16 v[8:11], v[152:155], v[218:221], v[8:11]
	v_mfma_f32_16x16x32_bf16 v[4:7], v[160:163], v[218:221], v[4:7]
	s_setprio 0
	s_barrier
	s_add_i32 vcc_hi, vcc_hi, 2
	s_add_u32 s70, s70, 0x100
	s_addc_u32 s71, s71, 0
	s_add_u32 s63, s63, 0x100
	s_addc_u32 vcc_lo, vcc_lo, 0
	s_cmp_gt_u32 vcc_hi, 13
	s_cbranch_scc0 .LBB0_920
	s_and_b64 vcc, exec, s[52:53]
	s_cbranch_vccz .LBB0_923
	s_barrier

	.amdhsa_kernel _Z6mk_fwd4Args
		.amdhsa_group_segment_fixed_size 0
		.amdhsa_private_segment_fixed_size 0
		.amdhsa_kernarg_size 480
		.amdhsa_user_sgpr_count 2
		.amdhsa_user_sgpr_dispatch_ptr 0
		.amdhsa_user_sgpr_queue_ptr 0
		.amdhsa_user_sgpr_kernarg_segment_ptr 1
		.amdhsa_user_sgpr_dispatch_id 0
		.amdhsa_user_sgpr_kernarg_preload_length 0
		.amdhsa_user_sgpr_kernarg_preload_offset 0
		.amdhsa_user_sgpr_private_segment_size 0
		.amdhsa_uses_dynamic_stack 0
		.amdhsa_enable_private_segment 0
		.amdhsa_system_sgpr_workgroup_id_x 1
		.amdhsa_system_sgpr_workgroup_id_y 0
		.amdhsa_system_sgpr_workgroup_id_z 0
		.amdhsa_system_sgpr_workgroup_info 0
		.amdhsa_system_vgpr_workitem_id 0
		.amdhsa_next_free_vgpr 256
		.amdhsa_next_free_sgpr 102
		.amdhsa_accum_offset 256
		.amdhsa_reserve_vcc 1
		.amdhsa_float_round_mode_32 0
		.amdhsa_float_round_mode_16_64 0
		.amdhsa_float_denorm_mode_32 3
		.amdhsa_float_denorm_mode_16_64 3
		.amdhsa_dx10_clamp 1
		.amdhsa_ieee_mode 1
		.amdhsa_fp16_overflow 0
		.amdhsa_tg_split 0
		.amdhsa_exception_fp_ieee_invalid_op 0
		.amdhsa_exception_fp_denorm_src 0
		.amdhsa_exception_fp_ieee_div_zero 0
		.amdhsa_exception_fp_ieee_overflow 0
		.amdhsa_exception_fp_ieee_underflow 0
		.amdhsa_exception_fp_ieee_inexact 0
		.amdhsa_exception_int_div_zero 0
	.end_amdhsa_kernel

amdhsa.kernels:
  - .agpr_count:     0
    .args:
      - .offset:         0
        .size:           224
        .value_kind:     by_value
      - .offset:         224
        .size:           4
        .value_kind:     hidden_block_count_x
      - .offset:         228
        .size:           4
        .value_kind:     hidden_block_count_y
      - .offset:         232
        .size:           4
        .value_kind:     hidden_block_count_z
      - .offset:         236
        .size:           2
        .value_kind:     hidden_group_size_x
      - .offset:         238
        .size:           2
        .value_kind:     hidden_group_size_y
      - .offset:         240
        .size:           2
        .value_kind:     hidden_group_size_z
      - .offset:         242
        .size:           2
        .value_kind:     hidden_remainder_x
      - .offset:         244
        .size:           2
        .value_kind:     hidden_remainder_y
      - .offset:         246
        .size:           2
        .value_kind:     hidden_remainder_z
      - .offset:         264
        .size:           8
        .value_kind:     hidden_global_offset_x
      - .offset:         272
        .size:           8
        .value_kind:     hidden_global_offset_y
      - .offset:         280
        .size:           8
        .value_kind:     hidden_global_offset_z
      - .offset:         288
        .size:           2
        .value_kind:     hidden_grid_dims
      - .offset:         344
        .size:           4
        .value_kind:     hidden_dynamic_lds_size
    .group_segment_fixed_size: 0
    .kernarg_segment_align: 8
    .kernarg_segment_size: 480
    .language:       OpenCL C
    .language_version:
      - 2
      - 0
    .max_flat_workgroup_size: 512
    .name:           _Z6mk_fwd4Args
    .private_segment_fixed_size: 0
    .sgpr_count:     108
    .sgpr_spill_count: 183
    .symbol:         _Z6mk_fwd4Args.kd
    .uniform_work_group_size: 1
    .uses_dynamic_stack: false
    .vgpr_count:     256
    .vgpr_spill_count: 0
    .wavefront_size: 64
